# bf16 GEMM epilogues: 28 more add-zero ops dropped by converting accumulator quads in place (high pair first)
# baseline (speedup 1.0000x reference)
; __device__ __forceinline__ unsigned cvt_pk_bf16(float lo, float hi) { typedef __bf16 bf2_t __attribute__((ext_vector_type(2))); const f32x2 v = {lo, hi}; return __builtin_bit_cast(unsigned, __builtin_convertvector(v, bf2_t)); }
;     __device__ __forceinline__ void operator()(const f32x4 (&acc)[2][2][4][2], const Unit& u, int wr, int wc, int fr, int fq, PG8_LAS unsigned char* lds) const {
;     ...
;             for (int m = 0; m < 4; ++m) { bf16_t* rowp = O + (size_t)(row0 + ai * HALF + m * 16) * ldc + col0;
; #pragma unroll
;                 for (int bj = 0; bj < 2; ++bj) { const f32x4 v0 = acc[ai][bj][m][0] * scale + bv[bj][0], v1 = acc[ai][bj][m][1] * scale + bv[bj][1];
;                     u32x4 w; w.x = cvt_pk_bf16(v0[0], v0[1]); w.y = cvt_pk_bf16(v0[2], v0[3]); w.z = cvt_pk_bf16(v1[0], v1[1]); w.w = cvt_pk_bf16(v1[2], v1[3]);
;                     *(u32x4*)(rowp + bj * HALF) = w; } }
.LBB0_173:
	v_lshl_add_u32 v140, s74, 8, v17
	v_lshl_or_b32 v134, s73, 8, v67
	v_mov_b64_e32 v[132:133], s[76:77]
	v_ashrrev_i32_e32 v135, 31, v134
	v_mad_i64_i32 v[136:137], s[38:39], v140, s75, v[132:133]
	v_lshlrev_b64 v[134:135], 1, v[134:135]
	v_lshl_add_u64 v[136:137], v[136:137], 0, v[134:135]
	v_cvt_pk_bf16_f32 v127, v126, v127
	v_cvt_pk_bf16_f32 v126, v124, v125
	v_cvt_pk_bf16_f32 v124, v128, v129
	v_cvt_pk_bf16_f32 v125, v130, v131
	global_store_dwordx4 v[136:137], v[124:127], off
	s_nop 1
	v_cvt_pk_bf16_f32 v111, v110, v111
	v_cvt_pk_bf16_f32 v110, v108, v109
	v_cvt_pk_bf16_f32 v108, v116, v117
	v_cvt_pk_bf16_f32 v109, v118, v119
	global_store_dwordx4 v[136:137], v[108:111], off offset:256
	s_nop 1
	v_add_u32_e32 v108, 16, v140
	v_mad_i64_i32 v[108:109], s[38:39], v108, s75, v[132:133]
	v_lshl_add_u64 v[116:117], v[108:109], 0, v[134:135]
	v_cvt_pk_bf16_f32 v108, v120, v121
	v_cvt_pk_bf16_f32 v109, v122, v123
	v_cvt_pk_bf16_f32 v110, v112, v113
	v_cvt_pk_bf16_f32 v111, v114, v115
	global_store_dwordx4 v[116:117], v[108:111], off
	s_nop 1
	v_cvt_pk_bf16_f32 v95, v94, v95
	v_cvt_pk_bf16_f32 v94, v92, v93
	v_cvt_pk_bf16_f32 v92, v100, v101
	v_cvt_pk_bf16_f32 v93, v102, v103
	global_store_dwordx4 v[116:117], v[92:95], off offset:256
	s_nop 1
	v_add_u32_e32 v92, 32, v140
	v_mad_i64_i32 v[92:93], s[38:39], v92, s75, v[132:133]
	v_lshl_add_u64 v[100:101], v[92:93], 0, v[134:135]
	v_cvt_pk_bf16_f32 v92, v104, v105
	v_cvt_pk_bf16_f32 v93, v106, v107
	v_cvt_pk_bf16_f32 v94, v96, v97
	v_cvt_pk_bf16_f32 v95, v98, v99
	global_store_dwordx4 v[100:101], v[92:95], off
	s_nop 1
	v_cvt_pk_bf16_f32 v79, v78, v79
	v_cvt_pk_bf16_f32 v78, v76, v77
	v_cvt_pk_bf16_f32 v76, v84, v85
	v_cvt_pk_bf16_f32 v77, v86, v87
	global_store_dwordx4 v[100:101], v[76:79], off offset:256
	s_nop 1
	v_add_u32_e32 v76, 48, v140
	v_mad_i64_i32 v[76:77], s[38:39], v76, s75, v[132:133]
	v_lshl_add_u64 v[84:85], v[76:77], 0, v[134:135]
	v_cvt_pk_bf16_f32 v76, v88, v89
	v_cvt_pk_bf16_f32 v77, v90, v91
	v_cvt_pk_bf16_f32 v78, v80, v81
	v_cvt_pk_bf16_f32 v79, v82, v83
	global_store_dwordx4 v[84:85], v[76:79], off
	s_nop 1
	v_cvt_pk_bf16_f32 v71, v70, v71
	v_cvt_pk_bf16_f32 v70, v68, v69
	v_cvt_pk_bf16_f32 v68, v72, v73
	v_cvt_pk_bf16_f32 v69, v74, v75
	global_store_dwordx4 v[84:85], v[68:71], off offset:256
	s_nop 1
	v_add_u32_e32 v68, 0x80, v140
	v_mad_i64_i32 v[68:69], s[38:39], v68, s75, v[132:133]
	v_lshl_add_u64 v[68:69], v[68:69], 0, v[134:135]
	v_cvt_pk_bf16_f32 v37, v36, v37
	v_cvt_pk_bf16_f32 v36, v34, v35
	v_cvt_pk_bf16_f32 v34, v46, v47
	v_cvt_pk_bf16_f32 v35, v48, v49
	global_store_dwordx4 v[68:69], v[34:37], off
	v_pk_add_f32 v[46:47], v[64:65], 0 op_sel_hi:[1,0]
	v_pk_add_f32 v[48:49], v[62:63], 0 op_sel_hi:[1,0]
	v_cvt_pk_bf16_f32 v34, v58, v59
	v_cvt_pk_bf16_f32 v35, v60, v61
	v_cvt_pk_bf16_f32 v36, v48, v49
	v_cvt_pk_bf16_f32 v37, v46, v47
	global_store_dwordx4 v[68:69], v[34:37], off offset:256
	s_nop 1
	v_add_u32_e32 v34, 0x90, v140
	v_mad_i64_i32 v[34:35], s[38:39], v34, s75, v[132:133]
	v_lshl_add_u64 v[34:35], v[34:35], 0, v[134:135]
	v_cvt_pk_bf16_f32 v21, v20, v21
	v_cvt_pk_bf16_f32 v20, v18, v19
	v_cvt_pk_bf16_f32 v18, v22, v23
	v_cvt_pk_bf16_f32 v19, v24, v25
	global_store_dwordx4 v[34:35], v[18:21], off
	v_pk_add_f32 v[22:23], v[56:57], 0 op_sel_hi:[1,0]
	v_pk_add_f32 v[24:25], v[54:55], 0 op_sel_hi:[1,0]
	s_and_b64 vcc, exec, s[40:41]
	v_cvt_pk_bf16_f32 v18, v50, v51
	v_cvt_pk_bf16_f32 v19, v52, v53
	v_cvt_pk_bf16_f32 v20, v24, v25
	v_cvt_pk_bf16_f32 v21, v22, v23
	global_store_dwordx4 v[34:35], v[18:21], off offset:256
	s_nop 1
	v_add_u32_e32 v18, 0xa0, v140
	v_mad_i64_i32 v[18:19], s[38:39], v18, s75, v[132:133]
	v_lshl_add_u64 v[18:19], v[18:19], 0, v[134:135]
	v_cvt_pk_bf16_f32 v11, v10, v11
	v_cvt_pk_bf16_f32 v10, v8, v9
	v_cvt_pk_bf16_f32 v8, v12, v13
	v_cvt_pk_bf16_f32 v9, v14, v15
	global_store_dwordx4 v[18:19], v[8:11], off
	v_pk_add_f32 v[12:13], v[44:45], 0 op_sel_hi:[1,0]
	v_pk_add_f32 v[14:15], v[42:43], 0 op_sel_hi:[1,0]
	s_nop 0
	v_cvt_pk_bf16_f32 v8, v38, v39
	v_cvt_pk_bf16_f32 v9, v40, v41
	v_cvt_pk_bf16_f32 v10, v14, v15
	v_cvt_pk_bf16_f32 v11, v12, v13
	global_store_dwordx4 v[18:19], v[8:11], off offset:256
	s_nop 1
	v_add_u32_e32 v8, 0xb0, v140
	v_mad_i64_i32 v[8:9], s[38:39], v8, s75, v[132:133]
	v_lshl_add_u64 v[8:9], v[8:9], 0, v[134:135]
	v_cvt_pk_bf16_f32 v3, v2, v3
	v_cvt_pk_bf16_f32 v2, v0, v1
	v_cvt_pk_bf16_f32 v0, v4, v5
	v_cvt_pk_bf16_f32 v1, v6, v7
	global_store_dwordx4 v[8:9], v[0:3], off
	v_pk_add_f32 v[4:5], v[32:33], 0 op_sel_hi:[1,0]
	v_pk_add_f32 v[6:7], v[30:31], 0 op_sel_hi:[1,0]
	s_mov_b64 s[38:39], -1
	v_cvt_pk_bf16_f32 v0, v26, v27
	v_cvt_pk_bf16_f32 v1, v28, v29
	v_cvt_pk_bf16_f32 v2, v6, v7
	v_cvt_pk_bf16_f32 v3, v4, v5
	global_store_dwordx4 v[8:9], v[0:3], off offset:256
	s_cbranch_vccnz .LBB0_152
	s_andn2_b64 vcc, exec, s[2:3]
	s_cbranch_vccnz .LBB0_151
	s_barrier
	s_branch .LBB0_151

; __device__ __forceinline__ unsigned cvt_pk_bf16(float lo, float hi) { typedef __bf16 bf2_t __attribute__((ext_vector_type(2))); const f32x2 v = {lo, hi}; return __builtin_bit_cast(unsigned, __builtin_convertvector(v, bf2_t)); }
;     __device__ __forceinline__ void operator()(const f32x4 (&acc)[2][2][4][2], const Unit& u, int wr, int wc, int fr, int fq, PG8_LAS unsigned char* lds) const {
;     ...
;             for (int m = 0; m < 4; ++m) { bf16_t* rowp = O + (size_t)(row0 + ai * HALF + m * 16) * ldc + col0;
; #pragma unroll
;                 for (int bj = 0; bj < 2; ++bj) { const f32x4 v0 = acc[ai][bj][m][0] * scale + bv[bj][0], v1 = acc[ai][bj][m][1] * scale + bv[bj][1];
;                     u32x4 w; w.x = cvt_pk_bf16(v0[0], v0[1]); w.y = cvt_pk_bf16(v0[2], v0[3]); w.z = cvt_pk_bf16(v1[0], v1[1]); w.w = cvt_pk_bf16(v1[2], v1[3]);
;                     *(u32x4*)(rowp + bj * HALF) = w; } }
.LBB0_737:
	v_lshl_add_u32 v132, s74, 8, v17
	v_lshl_or_b32 v134, s73, 8, v67
	v_readlane_b32 s38, v252, 9
	v_ashrrev_i32_e32 v133, 31, v132
	v_lshlrev_b64 v[132:133], 11, v[132:133]
	v_readlane_b32 s39, v252, 10
	v_ashrrev_i32_e32 v135, 31, v134
	v_lshl_add_u64 v[132:133], s[38:39], 0, v[132:133]
	v_lshl_add_u64 v[132:133], v[134:135], 1, v[132:133]
	v_cvt_pk_bf16_f32 v127, v126, v127
	v_cvt_pk_bf16_f32 v126, v124, v125
	v_cvt_pk_bf16_f32 v124, v128, v129
	v_cvt_pk_bf16_f32 v125, v130, v131
	global_store_dwordx4 v[132:133], v[124:127], off
	s_nop 1
	v_cvt_pk_bf16_f32 v111, v110, v111
	v_cvt_pk_bf16_f32 v110, v108, v109
	v_cvt_pk_bf16_f32 v108, v116, v117
	v_cvt_pk_bf16_f32 v109, v118, v119
	global_store_dwordx4 v[132:133], v[108:111], off offset:256
	s_nop 0
	s_mov_b32 s23, 0x8000
	v_cvt_pk_bf16_f32 v108, v120, v121
	v_cvt_pk_bf16_f32 v109, v122, v123
	v_cvt_pk_bf16_f32 v110, v112, v113
	v_add_co_u32_e32 v112, vcc, s23, v132
	v_cvt_pk_bf16_f32 v111, v114, v115
	s_nop 0
	v_addc_co_u32_e32 v113, vcc, 0, v133, vcc
	s_mov_b64 s[38:39], 0x8000
	global_store_dwordx4 v[112:113], v[108:111], off
	s_nop 1
	v_lshl_add_u64 v[116:117], v[132:133], 0, s[38:39]
	v_cvt_pk_bf16_f32 v95, v94, v95
	v_cvt_pk_bf16_f32 v94, v92, v93
	v_cvt_pk_bf16_f32 v92, v100, v101
	v_cvt_pk_bf16_f32 v93, v102, v103
	global_store_dwordx4 v[116:117], v[92:95], off offset:256
	s_nop 0
	s_mov_b32 s23, 0x10000
	v_cvt_pk_bf16_f32 v92, v104, v105
	v_cvt_pk_bf16_f32 v93, v106, v107
	v_cvt_pk_bf16_f32 v94, v96, v97
	v_add_co_u32_e32 v96, vcc, s23, v132
	v_cvt_pk_bf16_f32 v95, v98, v99
	s_nop 0
	v_addc_co_u32_e32 v97, vcc, 0, v133, vcc
	s_mov_b64 s[38:39], 0x10000
	global_store_dwordx4 v[96:97], v[92:95], off
	s_nop 1
	v_lshl_add_u64 v[100:101], v[132:133], 0, s[38:39]
	v_cvt_pk_bf16_f32 v79, v78, v79
	v_cvt_pk_bf16_f32 v78, v76, v77
	v_cvt_pk_bf16_f32 v76, v84, v85
	v_cvt_pk_bf16_f32 v77, v86, v87
	global_store_dwordx4 v[100:101], v[76:79], off offset:256
	s_nop 0
	s_mov_b32 s23, 0x18000
	v_cvt_pk_bf16_f32 v76, v88, v89
	v_cvt_pk_bf16_f32 v77, v90, v91
	v_cvt_pk_bf16_f32 v78, v80, v81
	v_add_co_u32_e32 v80, vcc, s23, v132
	v_cvt_pk_bf16_f32 v79, v82, v83
	s_nop 0
	v_addc_co_u32_e32 v81, vcc, 0, v133, vcc
	s_mov_b64 s[38:39], 0x18000
	global_store_dwordx4 v[80:81], v[76:79], off
	s_nop 1
	v_lshl_add_u64 v[84:85], v[132:133], 0, s[38:39]
	v_cvt_pk_bf16_f32 v71, v70, v71
	v_cvt_pk_bf16_f32 v70, v68, v69
	v_cvt_pk_bf16_f32 v68, v72, v73
	v_cvt_pk_bf16_f32 v69, v74, v75
	s_mov_b32 s23, 0x40000
	global_store_dwordx4 v[84:85], v[68:71], off offset:256
	s_nop 0
	s_mov_b64 s[38:39], 0x40000
	v_pk_add_f32 v[70:71], v[44:45], 0 op_sel_hi:[1,0]
	v_pk_add_f32 v[44:45], v[42:43], 0 op_sel_hi:[1,0]
	v_cvt_pk_bf16_f32 v42, v46, v47
	v_add_co_u32_e32 v46, vcc, s23, v132
	v_cvt_pk_bf16_f32 v43, v48, v49
	v_cvt_pk_bf16_f32 v44, v44, v45
	v_cvt_pk_bf16_f32 v45, v70, v71
	v_addc_co_u32_e32 v47, vcc, 0, v133, vcc
	global_store_dwordx4 v[46:47], v[42:45], off
	v_pk_add_f32 v[46:47], v[64:65], 0 op_sel_hi:[1,0]
	v_pk_add_f32 v[48:49], v[62:63], 0 op_sel_hi:[1,0]
	v_lshl_add_u64 v[68:69], v[132:133], 0, s[38:39]
	v_cvt_pk_bf16_f32 v42, v58, v59
	v_cvt_pk_bf16_f32 v43, v60, v61
	v_cvt_pk_bf16_f32 v44, v48, v49
	v_cvt_pk_bf16_f32 v45, v46, v47
	s_mov_b32 s23, 0x48000
	global_store_dwordx4 v[68:69], v[42:45], off offset:256
	s_nop 0
	s_mov_b64 s[38:39], 0x48000
	v_pk_add_f32 v[44:45], v[20:21], 0 op_sel_hi:[1,0]
	v_pk_add_f32 v[20:21], v[18:19], 0 op_sel_hi:[1,0]
	v_cvt_pk_bf16_f32 v18, v30, v31
	v_add_co_u32_e32 v30, vcc, s23, v132
	v_cvt_pk_bf16_f32 v19, v32, v33
	v_cvt_pk_bf16_f32 v20, v20, v21
	v_cvt_pk_bf16_f32 v21, v44, v45
	v_addc_co_u32_e32 v31, vcc, 0, v133, vcc
	global_store_dwordx4 v[30:31], v[18:21], off
	v_pk_add_f32 v[30:31], v[56:57], 0 op_sel_hi:[1,0]
	v_pk_add_f32 v[32:33], v[54:55], 0 op_sel_hi:[1,0]
	v_lshl_add_u64 v[42:43], v[132:133], 0, s[38:39]
	v_cvt_pk_bf16_f32 v18, v50, v51
	v_cvt_pk_bf16_f32 v19, v52, v53
	v_cvt_pk_bf16_f32 v20, v32, v33
	v_cvt_pk_bf16_f32 v21, v30, v31
	s_mov_b32 s23, 0x50000
	global_store_dwordx4 v[42:43], v[18:21], off offset:256
	s_nop 0
	s_mov_b64 s[38:39], 0x50000
	v_pk_add_f32 v[20:21], v[10:11], 0 op_sel_hi:[1,0]
	v_pk_add_f32 v[10:11], v[8:9], 0 op_sel_hi:[1,0]
	v_cvt_pk_bf16_f32 v8, v12, v13
	v_add_co_u32_e32 v12, vcc, s23, v132
	v_cvt_pk_bf16_f32 v9, v14, v15
	v_cvt_pk_bf16_f32 v10, v10, v11
	v_cvt_pk_bf16_f32 v11, v20, v21
	v_addc_co_u32_e32 v13, vcc, 0, v133, vcc
	global_store_dwordx4 v[12:13], v[8:11], off
	v_pk_add_f32 v[12:13], v[40:41], 0 op_sel_hi:[1,0]
	v_pk_add_f32 v[14:15], v[38:39], 0 op_sel_hi:[1,0]
	v_lshl_add_u64 v[18:19], v[132:133], 0, s[38:39]
	v_cvt_pk_bf16_f32 v8, v34, v35
	v_cvt_pk_bf16_f32 v9, v36, v37
	v_cvt_pk_bf16_f32 v10, v14, v15
	v_cvt_pk_bf16_f32 v11, v12, v13
	s_mov_b32 s23, 0x58000
	global_store_dwordx4 v[18:19], v[8:11], off offset:256
	s_nop 0
	s_mov_b64 s[38:39], 0x58000
	v_pk_add_f32 v[10:11], v[2:3], 0 op_sel_hi:[1,0]
	v_pk_add_f32 v[2:3], v[0:1], 0 op_sel_hi:[1,0]
	v_cvt_pk_bf16_f32 v0, v4, v5
	v_add_co_u32_e32 v4, vcc, s23, v132
	v_cvt_pk_bf16_f32 v1, v6, v7
	v_cvt_pk_bf16_f32 v2, v2, v3
	v_cvt_pk_bf16_f32 v3, v10, v11
	v_addc_co_u32_e32 v5, vcc, 0, v133, vcc
	global_store_dwordx4 v[4:5], v[0:3], off
	v_pk_add_f32 v[4:5], v[28:29], 0 op_sel_hi:[1,0]
	v_pk_add_f32 v[6:7], v[26:27], 0 op_sel_hi:[1,0]
	v_lshl_add_u64 v[8:9], v[132:133], 0, s[38:39]
	v_cvt_pk_bf16_f32 v0, v22, v23
	v_cvt_pk_bf16_f32 v1, v24, v25
	v_cvt_pk_bf16_f32 v2, v6, v7
	v_cvt_pk_bf16_f32 v3, v4, v5
	s_and_b64 vcc, exec, s[40:41]
	s_mov_b64 s[38:39], -1
	global_store_dwordx4 v[8:9], v[0:3], off offset:256
	s_cbranch_vccnz .LBB0_712
	s_andn2_b64 vcc, exec, s[2:3]
	s_cbranch_vccnz .LBB0_711
	s_barrier
	s_branch .LBB0_711
